# oddprep row pass: per-lane gain vectors loaded once before the row loop instead of re-loaded and waited for (vmcnt(0)) nine times per row
# speedup vs baseline: 1.0058x; 1.0058x over previous
; DEVI unsigned pk_bf16(float lo, float hi) { unsigned r; asm("v_cvt_pk_bf16_f32 %0, %1, %2" : "=v"(r) : "v"(lo), "v"(hi)); return r; }
; __device__ __forceinline__ void oddprep_phase(const Params& p) {
;   const int tid = otid(); const int lane = tid & 63, wave = (obid() * NT + tid) >> 6, nw = gridDim.x * (NT / 64);
;   bf16_t* Zo = (bf16_t*)(p.ws + OFF_Z);
;   float* G = (float*)(p.ws + OFF_GATES);
;   bf16_t* KR = (bf16_t*)(p.ws + OFF_KR);
;   float* ROPE = (float*)(p.ws + OFF_ROPE);
;   for (int r = wave; r < M; r += nw) {
;     ...
;       for (int j = 0; j < 3; ++j) { const float* gp = p.od_g_qa + 128 * j + 2 * lane; *(unsigned*)(zr + 128 * j + 2 * lane) = pk_bf16(bf_lo(u[j]) * rs * gp[0], bf_hi(u[j]) * rs * gp[1]); }
;     }
;     {
;       const uint2 u = *(const uint2*)(zr + 384 + 4 * lane);
;       float v0 = bf_lo(u.x), v1 = bf_hi(u.x), v2 = bf_lo(u.y), v3 = bf_hi(u.y);
;       float ss = wave_sum(v0 * v0 + v1 * v1 + v2 * v2 + v3 * v3); const float rs = rsqrtf(ss * (1.0f / 256.0f) + EPS);
;       const float* gp = p.od_g_kva + 4 * lane; uint2 o; o.x = pk_bf16(v0 * rs * gp[0], v1 * rs * gp[1]); o.y = pk_bf16(v2 * rs * gp[2], v3 * rs * gp[3]);
;       *(uint2*)(zr + 384 + 4 * lane) = o;
;     }
;     {
;       const int b = r / T, t = r - b * T;
;       const int pos = t < 16 ? t : p.pos[b * 4096 + (t - 16)] + 16;
;       const int i = lane & 15;
;       const float freq = exp2f(-(float)i * 0.8304820237218406f);
;       const float ang = (float)pos * freq;
;       double rev = (double)ang * 0.15915494309189535; rev -= rint(rev);
;       const float rf = (float)rev;
;       const float cs = __builtin_amdgcn_cosf(rf), sn = __builtin_amdgcn_sinf(rf);
;       float v = lane < 32 ? bf2f(zr[640 + lane]) : 0.f;
;       const float ss = wave_sum(v * v); const float rs = rsqrtf(ss * (1.0f / 32.0f) + EPS);
;       const float kn = lane < 32 ? v * rs * p.od_g_kr[lane & 31] : 0.f;
;       const float pt = __shfl_xor(kn, 16);
;       const float o = lane < 16 ? kn * cs - pt * sn : pt * sn + kn * cs;
;       if (lane < 32) KR[(size_t)r * 32 + lane] = f2bf(o);
;       if (lane < 16) { ROPE[(size_t)r * 32 + lane] = cs; ROPE[(size_t)r * 32 + 16 + lane] = sn; }
;     }
; #pragma unroll
;     for (int which = 0; which < 2; ++which) {
;       bf16_t* base = zr + (which ? 1184 : 672) + 8 * lane; const float* gg = (which ? p.od_g_fk : p.od_g_fq) + 8 * (lane & 7);
.LBB0_1260:
	s_or_b64 exec, exec, s[0:1]
	s_waitcnt lgkmcnt(0)
	v_mov_b32_e32 v0, v128
	v_readlane_b32 s0, v254, 22
	s_barrier
	s_nop 0
	v_lshl_add_u32 v1, s0, 9, v0
	v_ashrrev_i32_e32 v4, 6, v1
	v_cmp_gt_i32_e32 vcc, s22, v4
	s_and_saveexec_b64 s[0:1], vcc
	s_cbranch_execz .LBB0_1275
	v_cmp_lt_i32_e32 vcc, v185, v184
	s_mov_b32 s2, 0xc2fc0000
	v_and_b32_e32 v1, 63, v0
	v_cndmask_b32_e32 v5, v183, v185, vcc
	v_cmp_lt_i32_e32 vcc, v186, v184
	v_lshlrev_b32_e32 v38, 2, v5
	v_readlane_b32 s36, v253, 44
	v_cndmask_b32_e32 v5, v183, v186, vcc
	v_cmp_lt_i32_e32 vcc, v187, v184
	v_lshlrev_b32_e32 v39, 2, v5
	v_lshlrev_b32_e32 v2, 1, v1
	v_cndmask_b32_e32 v5, v183, v187, vcc
	v_cmp_lt_i32_e32 vcc, v191, v184
	v_lshlrev_b32_e32 v40, 2, v5
	v_lshlrev_b32_e32 v26, 2, v1
	v_cndmask_b32_e32 v5, v183, v191, vcc
	v_cmp_lt_i32_e32 vcc, v192, v184
	v_lshlrev_b32_e32 v41, 2, v5
	v_cmp_gt_u32_e64 s[4:5], 16, v1
	v_cndmask_b32_e32 v5, v183, v192, vcc
	v_cmp_lt_i32_e32 vcc, v190, v184
	v_lshlrev_b32_e32 v42, 2, v5
	v_lshlrev_b32_e32 v24, 3, v1
	v_cndmask_b32_e32 v5, v183, v190, vcc
	v_lshlrev_b32_e32 v43, 2, v5
	v_and_b32_e32 v5, 15, v0
	v_cvt_f32_ubyte0_e32 v5, v5
	v_mul_f32_e32 v6, 0xbf549a78, v5
	v_cmp_gt_f32_e32 vcc, s2, v6
	v_mov_b32_e32 v6, 0x42800000
	v_lshlrev_b32_e32 v0, 5, v0
	v_cndmask_b32_e32 v6, 0, v6, vcc
	v_fmac_f32_e32 v6, 0xbf549a78, v5
	v_exp_f32_e32 v5, v6
	v_not_b32_e32 v6, 63
	v_cndmask_b32_e32 v6, 0, v6, vcc
	v_cmp_gt_u32_e64 s[2:3], 32, v1
	v_ldexp_f32 v44, v5, v6
	v_cmp_gt_u32_e64 s[6:7], 8, v1
	v_lshlrev_b32_e32 v30, 4, v1
	v_readlane_b32 s40, v253, 48
	v_readlane_b32 s41, v253, 49
	v_readlane_b32 s42, v253, 50
	v_readlane_b32 s43, v253, 51
	v_and_b32_e32 v0, 0xe0, v0
	v_mov_b32_e32 v1, v130
	v_ashrrev_i32_e32 v5, 31, v4
	v_mov_b32_e32 v3, v130
	v_lshl_add_u64 v[12:13], s[40:41], 0, v[0:1]
	v_lshl_add_u64 v[14:15], s[42:43], 0, v[0:1]
	v_lshlrev_b64 v[0:1], 6, v[4:5]
	v_lshl_add_u64 v[0:1], v[0:1], 0, v[2:3]
	s_mov_b64 s[8:9], 0x17a95900
	v_mov_b32_e32 v27, v130
	v_lshl_add_u64 v[18:19], v[0:1], 0, s[8:9]
	v_lshlrev_b64 v[0:1], 7, v[4:5]
	v_lshl_add_u64 v[20:21], v[0:1], 0, v[26:27]
	v_lshlrev_b64 v[0:1], 5, v[4:5]
	v_lshl_add_u64 v[0:1], v[0:1], 0, v[26:27]
	s_mov_b64 s[8:9], 0x3710000
	v_mov_b32_e32 v25, v130
	v_readlane_b32 s38, v253, 46
	v_readlane_b32 s39, v253, 47
	v_lshl_add_u64 v[22:23], v[0:1], 0, s[8:9]
	v_mad_i64_i32 v[0:1], s[8:9], v4, s53, 0
	v_lshl_add_u64 v[6:7], s[68:69], 0, v[24:25]
	v_mov_b32_e32 v31, v130
	v_lshl_add_u64 v[10:11], s[38:39], 0, v[26:27]
	v_lshl_add_u64 v[16:17], s[66:67], 0, v[26:27]
	v_or_b32_e32 v24, v0, v24
	v_or_b32_e32 v26, v0, v26
	v_or_b32_e32 v0, v0, v2
	s_mov_b64 s[8:9], 0x7895e00
	v_lshl_add_u64 v[8:9], s[70:71], 0, v[30:31]
	v_lshl_add_u64 v[28:29], v[0:1], 0, s[8:9]
	v_mad_i64_i32 v[30:31], s[8:9], v4, s53, v[30:31]
	v_mov_b32_e32 v25, v1
	v_mov_b32_e32 v27, v1
	s_mov_b64 s[8:9], 0
	v_readlane_b32 s37, v253, 45
	v_readlane_b32 s44, v253, 52
	v_readlane_b32 s45, v253, 53
	v_readlane_b32 s46, v253, 54
	v_readlane_b32 s47, v253, 55
	v_readlane_b32 s48, v253, 56
	v_readlane_b32 s49, v253, 57
	v_readlane_b32 s50, v253, 58
	v_readlane_b32 s51, v253, 59
	global_load_dwordx2 v[64:65], v[6:7], off
	global_load_dwordx2 v[66:67], v[6:7], off offset:512
	global_load_dwordx2 v[68:69], v[6:7], off offset:1024
	global_load_dwordx4 v[72:75], v[8:9], off
	global_load_dword v70, v[10:11], off
	global_load_dwordx4 v[76:79], v[12:13], off
	global_load_dwordx4 v[80:83], v[12:13], off offset:16
	global_load_dwordx4 v[84:87], v[14:15], off
	global_load_dwordx4 v[88:91], v[14:15], off offset:16
	s_waitcnt vmcnt(0)
	s_branch .LBB0_1263

; DEVI unsigned pk_bf16(float lo, float hi) { unsigned r; asm("v_cvt_pk_bf16_f32 %0, %1, %2" : "=v"(r) : "v"(lo), "v"(hi)); return r; }
; DEVI float bf_lo(unsigned u) { return __uint_as_float(u << 16); }
; DEVI float bf_hi(unsigned u) { return __uint_as_float(u & 0xffff0000u); }
; DEVI float wave_sum(float v) { for (int o = 32; o; o >>= 1) v += __shfl_xor(v, o); return v; }
; __device__ __forceinline__ void oddprep_phase(const Params& p) {
;     ...
;     {
;       unsigned u[3]; float ss = 0.f;
; #pragma unroll
;       for (int j = 0; j < 3; ++j) { u[j] = *(const unsigned*)(zr + 128 * j + 2 * lane); ss += bf_lo(u[j]) * bf_lo(u[j]) + bf_hi(u[j]) * bf_hi(u[j]); }
;       ss = wave_sum(ss); const float rs = rsqrtf(ss * (1.0f / 384.0f) + EPS);
; #pragma unroll
;       for (int j = 0; j < 3; ++j) { const float* gp = p.od_g_qa + 128 * j + 2 * lane; *(unsigned*)(zr + 128 * j + 2 * lane) = pk_bf16(bf_lo(u[j]) * rs * gp[0], bf_hi(u[j]) * rs * gp[1]); }
;     }
;     {
;       const uint2 u = *(const uint2*)(zr + 384 + 4 * lane);
;       float v0 = bf_lo(u.x), v1 = bf_hi(u.x), v2 = bf_lo(u.y), v3 = bf_hi(u.y);
;       float ss = wave_sum(v0 * v0 + v1 * v1 + v2 * v2 + v3 * v3); const float rs = rsqrtf(ss * (1.0f / 256.0f) + EPS);
;       const float* gp = p.od_g_kva + 4 * lane; uint2 o; o.x = pk_bf16(v0 * rs * gp[0], v1 * rs * gp[1]); o.y = pk_bf16(v2 * rs * gp[2], v3 * rs * gp[3]);
;       *(uint2*)(zr + 384 + 4 * lane) = o;
;     }
;     {
;       const int b = r / T, t = r - b * T;
;       const int pos = t < 16 ? t : p.pos[b * 4096 + (t - 16)] + 16;
.LBB0_1263:
	v_readlane_b32 s16, v253, 2
	v_readlane_b32 s18, v253, 4
	v_readlane_b32 s19, v253, 5
	s_mov_b32 s10, 0x7895000
	v_readlane_b32 s17, v253, 3
	v_lshl_add_u64 v[0:1], s[18:19], 0, v[26:27]
	v_add_co_u32_e32 v0, vcc, 0x7895000, v0
	s_nop 1
	v_addc_co_u32_e32 v1, vcc, 0, v1, vcc
	global_load_dword v5, v[0:1], off offset:2304
	global_load_dword v3, v[0:1], off offset:2560
	global_load_dword v36, v[0:1], off offset:2816
	s_waitcnt vmcnt(2)
	v_lshlrev_b32_e32 v34, 16, v5
	s_waitcnt vmcnt(1)
	v_lshlrev_b32_e32 v2, 16, v3
	v_and_b32_e32 v3, 0xffff0000, v3
	s_waitcnt vmcnt(0)
	v_lshlrev_b32_e32 v35, 16, v36
	v_and_b32_e32 v37, 0xffff0000, v36
	v_and_b32_e32 v36, 0xffff0000, v5
	v_pk_mul_f32 v[32:33], v[2:3], v[2:3]
	v_pk_mul_f32 v[46:47], v[36:37], v[36:37]
	v_add_f32_e32 v5, v32, v33
	v_pk_fma_f32 v[46:47], v[34:35], v[34:35], v[46:47]
	s_nop 0
	v_add_f32_e32 v5, v46, v5
	v_add_f32_e32 v5, v5, v47
	ds_bpermute_b32 v32, v38, v5
	s_waitcnt lgkmcnt(0)
	v_add_f32_e32 v5, v5, v32
	ds_bpermute_b32 v32, v39, v5
	s_waitcnt lgkmcnt(0)
	v_add_f32_e32 v5, v5, v32
	ds_bpermute_b32 v32, v40, v5
	s_waitcnt lgkmcnt(0)
	v_add_f32_e32 v5, v5, v32
	ds_bpermute_b32 v32, v41, v5
	s_waitcnt lgkmcnt(0)
	v_add_f32_e32 v5, v5, v32
	ds_bpermute_b32 v32, v42, v5
	s_waitcnt lgkmcnt(0)
	v_add_f32_e32 v5, v5, v32
	ds_bpermute_b32 v32, v43, v5
	s_waitcnt lgkmcnt(0)
	v_add_f32_e32 v5, v5, v32
	v_fmamk_f32 v5, v5, 0x3b2aaaab, v132
	v_cmp_gt_f32_e32 vcc, s81, v5
	v_mul_f32_e32 v32, 0x4b800000, v5
	s_nop 0
	v_cndmask_b32_e32 v5, v5, v32, vcc
	v_rsq_f32_e32 v5, v5
	s_nop 0
	v_mul_f32_e32 v32, 0x45800000, v5
	v_cndmask_b32_e32 v5, v5, v32, vcc
	v_mul_f32_e32 v34, v5, v34
	v_mul_f32_e32 v2, v5, v2
	v_mul_f32_e32 v3, v5, v3
	s_nop 1
	v_mov_b64_e32 v[32:33], v[64:65]
	v_mul_f32_e32 v32, v32, v34
	v_mul_f32_e32 v34, v5, v36
	v_mul_f32_e32 v33, v33, v34
	v_cvt_pk_bf16_f32 v32, v32, v33
	global_store_dword v[0:1], v32, off offset:2304
	s_nop 1
	v_mov_b64_e32 v[32:33], v[66:67]
	v_mul_f32_e32 v2, v32, v2
	v_mul_f32_e32 v3, v33, v3
	v_cvt_pk_bf16_f32 v2, v2, v3
	global_store_dword v[0:1], v2, off offset:2560
	v_mul_f32_e32 v32, v5, v35
	v_mul_f32_e32 v5, v5, v37
	s_nop 1
	v_mov_b64_e32 v[2:3], v[68:69]
	v_mul_f32_e32 v2, v2, v32
	v_mul_f32_e32 v3, v3, v5
	v_cvt_pk_bf16_f32 v2, v2, v3
	global_store_dword v[0:1], v2, off offset:2816
	v_lshl_add_u64 v[0:1], s[18:19], 0, v[24:25]
	v_add_co_u32_e32 v32, vcc, s10, v0
	s_nop 1
	v_addc_co_u32_e32 v33, vcc, 0, v1, vcc
	global_load_dwordx2 v[0:1], v[32:33], off offset:3072
	s_waitcnt vmcnt(0)
	v_lshlrev_b32_e32 v34, 16, v0
	v_and_b32_e32 v35, 0xffff0000, v0
	v_lshlrev_b32_e32 v37, 16, v1
	v_and_b32_e32 v36, 0xffff0000, v1
	v_pk_mul_f32 v[0:1], v[34:35], v[34:35]
	v_pk_mul_f32 v[2:3], v[36:37], v[36:37]
	v_add_f32_e32 v0, v0, v1
	v_add_f32_e32 v0, v0, v3
	v_add_f32_e32 v0, v2, v0
	ds_bpermute_b32 v1, v38, v0
	s_waitcnt lgkmcnt(0)
	v_add_f32_e32 v0, v0, v1
	ds_bpermute_b32 v1, v39, v0
	s_waitcnt lgkmcnt(0)
	v_add_f32_e32 v0, v0, v1
	ds_bpermute_b32 v1, v40, v0
	s_waitcnt lgkmcnt(0)
	v_add_f32_e32 v0, v0, v1
	ds_bpermute_b32 v1, v41, v0
	s_waitcnt lgkmcnt(0)
	v_add_f32_e32 v0, v0, v1
	ds_bpermute_b32 v1, v42, v0
	s_waitcnt lgkmcnt(0)
	v_add_f32_e32 v0, v0, v1
	ds_bpermute_b32 v1, v43, v0
	s_waitcnt lgkmcnt(0)
	v_add_f32_e32 v0, v0, v1
	v_fmamk_f32 v0, v0, 0x3b800000, v132
	v_cmp_gt_f32_e32 vcc, s81, v0
	v_mul_f32_e32 v1, 0x4b800000, v0
	s_nop 0
	v_cndmask_b32_e32 v0, v0, v1, vcc
	v_rsq_f32_e32 v0, v0
	s_nop 0
	v_mul_f32_e32 v1, 0x45800000, v0
	v_cndmask_b32_e32 v5, v0, v1, vcc
	v_mul_f32_e32 v34, v5, v34
	s_nop 1
	v_mov_b64_e32 v[0:1], v[72:73]
	v_mov_b64_e32 v[2:3], v[74:75]
	v_mul_f32_e32 v0, v0, v34
	v_mul_f32_e32 v34, v5, v35
	v_mul_f32_e32 v1, v1, v34
	v_cvt_pk_bf16_f32 v0, v0, v1
	v_mul_f32_e32 v1, v5, v37
	v_mul_f32_e32 v1, v2, v1
	v_mul_f32_e32 v2, v5, v36
	v_mul_f32_e32 v2, v3, v2
	v_cvt_pk_bf16_f32 v1, v1, v2
	global_store_dwordx2 v[32:33], v[0:1], off offset:3072
	v_mul_hi_i32 v0, v4, s23
	v_lshrrev_b32_e32 v1, 31, v0
	v_ashrrev_i32_e32 v0, 11, v0
	v_add_u32_e32 v1, v0, v1
	v_mad_i32_i24 v0, v1, s24, v4
	v_cmp_lt_i32_e32 vcc, 15, v0
	s_and_saveexec_b64 s[10:11], vcc
	s_cbranch_execz .LBB0_1265
	v_mul_i32_i24_e32 v0, 0xffffeff0, v1
	v_lshl_add_u32 v0, v1, 12, v0
	v_add3_u32 v0, v4, v0, -16
	v_readlane_b32 s36, v253, 28
	v_ashrrev_i32_e32 v1, 31, v0
	v_readlane_b32 s38, v253, 30
	v_readlane_b32 s39, v253, 31
	v_readlane_b32 s37, v253, 29
	v_readlane_b32 s40, v253, 32
	v_lshl_add_u64 v[0:1], v[0:1], 2, s[38:39]
	global_load_dword v0, v[0:1], off
	v_readlane_b32 s41, v253, 33
	v_readlane_b32 s42, v253, 34
	v_readlane_b32 s43, v253, 35
	v_readlane_b32 s44, v253, 36
	v_readlane_b32 s45, v253, 37
	v_readlane_b32 s46, v253, 38
	v_readlane_b32 s47, v253, 39
	v_readlane_b32 s48, v253, 40
	v_readlane_b32 s49, v253, 41
	v_readlane_b32 s50, v253, 42
	v_readlane_b32 s51, v253, 43
	s_waitcnt vmcnt(0)
	v_add_u32_e32 v0, 16, v0

; DEVI float bf2f(bf16_t v) { return __uint_as_float(((unsigned)v) << 16); }
; DEVI float wave_sum(float v) { for (int o = 32; o; o >>= 1) v += __shfl_xor(v, o); return v; }
; __device__ __forceinline__ void oddprep_phase(const Params& p) {
;     ...
;       float v = lane < 32 ? bf2f(zr[640 + lane]) : 0.f;
;       const float ss = wave_sum(v * v); const float rs = rsqrtf(ss * (1.0f / 32.0f) + EPS);
;       const float kn = lane < 32 ? v * rs * p.od_g_kr[lane & 31] : 0.f;
.LBB0_1267:
	s_or_b64 exec, exec, s[10:11]
	v_mul_f32_e32 v3, v2, v2
	ds_bpermute_b32 v3, v38, v3
	s_waitcnt lgkmcnt(0)
	v_fmac_f32_e32 v3, v2, v2
	ds_bpermute_b32 v5, v39, v3
	s_waitcnt lgkmcnt(0)
	v_add_f32_e32 v3, v3, v5
	ds_bpermute_b32 v5, v40, v3
	s_waitcnt lgkmcnt(0)
	v_add_f32_e32 v3, v3, v5
	ds_bpermute_b32 v5, v41, v3
	s_waitcnt lgkmcnt(0)
	v_add_f32_e32 v3, v3, v5
	ds_bpermute_b32 v5, v42, v3
	s_waitcnt lgkmcnt(0)
	v_add_f32_e32 v3, v3, v5
	ds_bpermute_b32 v5, v43, v3
	s_and_saveexec_b64 s[10:11], s[2:3]
	s_cbranch_execz .LBB0_1269
	s_waitcnt lgkmcnt(0)
	v_add_f32_e32 v1, v3, v5
	v_fmamk_f32 v1, v1, 0x3d000000, v132
	v_cmp_gt_f32_e32 vcc, s81, v1
	v_mul_f32_e32 v3, 0x4b800000, v1
	s_nop 0
	v_cndmask_b32_e32 v1, v1, v3, vcc
	v_rsq_f32_e32 v1, v1
	s_nop 0
	v_mul_f32_e32 v3, 0x45800000, v1
	v_cndmask_b32_e32 v1, v1, v3, vcc
	v_mul_f32_e32 v1, v2, v1
	s_nop 1
	v_mov_b32_e32 v2, v70
	v_mul_f32_e32 v1, v1, v2

; DEVI unsigned pk_bf16(float lo, float hi) { unsigned r; asm("v_cvt_pk_bf16_f32 %0, %1, %2" : "=v"(r) : "v"(lo), "v"(hi)); return r; }
; DEVI float bf_lo(unsigned u) { return __uint_as_float(u << 16); }
; DEVI float bf_hi(unsigned u) { return __uint_as_float(u & 0xffff0000u); }
; DEVI float logsigmoidf_(float x) { return fminf(x, 0.f) - 0.6931471805599453f * __builtin_amdgcn_logf(1.0f + __builtin_amdgcn_exp2f(-fabsf(x) * LOG2E)); }
; __device__ __forceinline__ void oddprep_phase(const Params& p) {
;     ...
; #pragma unroll
;     for (int which = 0; which < 2; ++which) {
;       bf16_t* base = zr + (which ? 1184 : 672) + 8 * lane; const float* gg = (which ? p.od_g_fk : p.od_g_fq) + 8 * (lane & 7);
;       const uint4 u = *(const uint4*)base; const unsigned uu[4] = {u.x, u.y, u.z, u.w};
;       float v[8]; float ss = 0.f;
; #pragma unroll
;       for (int j = 0; j < 4; ++j) { v[2 * j] = bf_lo(uu[j]); v[2 * j + 1] = bf_hi(uu[j]); ss += v[2 * j] * v[2 * j] + v[2 * j + 1] * v[2 * j + 1]; }
;       ss += __shfl_xor(ss, 1); ss += __shfl_xor(ss, 2); ss += __shfl_xor(ss, 4);
;       const float rs = rsqrtf(ss * (1.0f / 64.0f) + EPS);
;       *(uint4*)base = make_uint4(pk_bf16(v[0] * rs * gg[0], v[1] * rs * gg[1]), pk_bf16(v[2] * rs * gg[2], v[3] * rs * gg[3]), pk_bf16(v[4] * rs * gg[4], v[5] * rs * gg[5]), pk_bf16(v[6] * rs * gg[6], v[7] * rs * gg[7]));
;     }
;     if (lane < 8) { float* gp = G + (size_t)r * 8 + lane; *gp = logsigmoidf_(*gp + p.od_b_f[lane]); }
.LBB0_1273:
	s_or_b64 exec, exec, s[10:11]
	v_readlane_b32 s16, v253, 2
	v_readlane_b32 s18, v253, 4
	v_readlane_b32 s19, v253, 5
	s_mov_b32 s10, 0x7896000
	v_readlane_b32 s17, v253, 3
	v_lshl_add_u64 v[0:1], s[18:19], 0, v[30:31]
	v_add_co_u32_e32 v2, vcc, 0x7895000, v0
	s_waitcnt lgkmcnt(0)
	s_nop 0
	v_addc_co_u32_e32 v3, vcc, 0, v1, vcc
	global_load_dwordx4 v[32:35], v[2:3], off offset:3648
	s_waitcnt vmcnt(0)
	v_and_b32_e32 v47, 0xffff0000, v33
	v_and_b32_e32 v46, 0xffff0000, v32
	v_lshlrev_b32_e32 v37, 16, v33
	v_lshlrev_b32_e32 v36, 16, v32
	v_pk_mul_f32 v[32:33], v[46:47], v[46:47]
	v_and_b32_e32 v51, 0xffff0000, v35
	v_and_b32_e32 v50, 0xffff0000, v34
	v_pk_fma_f32 v[32:33], v[36:37], v[36:37], v[32:33]
	v_lshlrev_b32_e32 v49, 16, v35
	v_lshlrev_b32_e32 v48, 16, v34
	v_pk_mul_f32 v[34:35], v[50:51], v[50:51]
	v_add_f32_e32 v5, v32, v33
	v_pk_fma_f32 v[34:35], v[48:49], v[48:49], v[34:35]
	s_nop 0
	v_add_f32_e32 v5, v5, v34
	v_add_f32_e32 v5, v5, v35
	ds_bpermute_b32 v32, v43, v5
	s_waitcnt lgkmcnt(0)
	v_add_f32_e32 v5, v5, v32
	ds_bpermute_b32 v32, v42, v5
	s_waitcnt lgkmcnt(0)
	v_add_f32_e32 v5, v5, v32
	ds_bpermute_b32 v32, v41, v5
	s_waitcnt lgkmcnt(0)
	v_add_f32_e32 v5, v5, v32
	v_fmamk_f32 v5, v5, 0x3c800000, v132
	v_cmp_gt_f32_e32 vcc, s81, v5
	v_mul_f32_e32 v32, 0x4b800000, v5
	s_nop 0
	v_cndmask_b32_e32 v5, v5, v32, vcc
	v_rsq_f32_e32 v5, v5
	s_nop 0
	v_mul_f32_e32 v32, 0x45800000, v5
	v_cndmask_b32_e32 v5, v5, v32, vcc
	v_mul_f32_e32 v36, v5, v36
	v_mul_f32_e32 v45, v5, v48
	s_nop 1
	v_mov_b64_e32 v[32:33], v[76:77]
	v_mov_b64_e32 v[34:35], v[78:79]
	v_mul_f32_e32 v32, v32, v36
	v_mul_f32_e32 v36, v5, v46
	v_mul_f32_e32 v33, v33, v36
	v_cvt_pk_bf16_f32 v32, v32, v33
	v_mul_f32_e32 v33, v5, v37
	v_mul_f32_e32 v33, v34, v33
	v_mul_f32_e32 v34, v5, v47
	v_mul_f32_e32 v34, v35, v34
	v_cvt_pk_bf16_f32 v33, v33, v34
	s_nop 1
	v_mov_b64_e32 v[34:35], v[80:81]
	v_mov_b64_e32 v[36:37], v[82:83]
	v_mul_f32_e32 v34, v34, v45
	v_mul_f32_e32 v45, v5, v50
	v_mul_f32_e32 v35, v35, v45
	v_cvt_pk_bf16_f32 v34, v34, v35
	v_mul_f32_e32 v35, v5, v49
	v_mul_f32_e32 v35, v36, v35
	v_mul_f32_e32 v5, v5, v51
	v_mul_f32_e32 v5, v37, v5
	v_cvt_pk_bf16_f32 v35, v35, v5
	global_store_dwordx4 v[2:3], v[32:35], off offset:3648
	s_nop 1
	v_add_co_u32_e32 v32, vcc, s10, v0
	s_nop 1
	v_addc_co_u32_e32 v33, vcc, 0, v1, vcc
	global_load_dwordx4 v[0:3], v[32:33], off offset:576
	s_waitcnt vmcnt(0)
	v_lshlrev_b32_e32 v37, 16, v1
	v_lshlrev_b32_e32 v36, 16, v0
	v_and_b32_e32 v1, 0xffff0000, v1
	v_and_b32_e32 v0, 0xffff0000, v0
	v_pk_mul_f32 v[34:35], v[0:1], v[0:1]
	s_nop 0
	v_pk_fma_f32 v[46:47], v[36:37], v[36:37], v[34:35]
	v_lshlrev_b32_e32 v35, 16, v3
	v_lshlrev_b32_e32 v34, 16, v2
	v_and_b32_e32 v3, 0xffff0000, v3
	v_and_b32_e32 v2, 0xffff0000, v2
	v_pk_mul_f32 v[48:49], v[2:3], v[2:3]
	v_add_f32_e32 v5, v46, v47
	v_pk_fma_f32 v[48:49], v[34:35], v[34:35], v[48:49]
	s_nop 0
	v_add_f32_e32 v5, v5, v48
	v_add_f32_e32 v5, v5, v49
	ds_bpermute_b32 v45, v43, v5
	s_waitcnt lgkmcnt(0)
	v_add_f32_e32 v5, v5, v45
	ds_bpermute_b32 v45, v42, v5
	s_waitcnt lgkmcnt(0)
	v_add_f32_e32 v5, v5, v45
	ds_bpermute_b32 v45, v41, v5
	s_waitcnt lgkmcnt(0)
	v_add_f32_e32 v5, v5, v45
	v_fmamk_f32 v5, v5, 0x3c800000, v132
	v_cmp_gt_f32_e32 vcc, s81, v5
	v_mul_f32_e32 v45, 0x4b800000, v5
	s_nop 0
	v_cndmask_b32_e32 v5, v5, v45, vcc
	v_rsq_f32_e32 v5, v5
	s_nop 0
	v_mul_f32_e32 v45, 0x45800000, v5
	v_cndmask_b32_e32 v5, v5, v45, vcc
	v_mul_f32_e32 v36, v5, v36
	v_mul_f32_e32 v0, v5, v0
	v_mul_f32_e32 v1, v5, v1
	v_mul_f32_e32 v34, v5, v34
	v_mul_f32_e32 v2, v5, v2
	v_mul_f32_e32 v3, v5, v3
	s_nop 1
	v_mov_b64_e32 v[46:47], v[84:85]
	v_mov_b64_e32 v[48:49], v[86:87]
	v_mul_f32_e32 v36, v46, v36
	v_mul_f32_e32 v0, v47, v0
	v_cvt_pk_bf16_f32 v0, v36, v0
	v_mul_f32_e32 v36, v5, v37
	v_mul_f32_e32 v36, v48, v36
	v_mul_f32_e32 v1, v49, v1
	v_cvt_pk_bf16_f32 v1, v36, v1
	s_nop 1
	v_mov_b64_e32 v[46:47], v[88:89]
	v_mov_b64_e32 v[48:49], v[90:91]
	v_mul_f32_e32 v34, v46, v34
	v_mul_f32_e32 v2, v47, v2
	v_cvt_pk_bf16_f32 v2, v34, v2
	v_mul_f32_e32 v34, v5, v35
	v_mul_f32_e32 v3, v49, v3
	v_mul_f32_e32 v34, v48, v34
	v_cvt_pk_bf16_f32 v3, v34, v3
	global_store_dwordx4 v[32:33], v[0:3], off offset:576
	s_and_saveexec_b64 s[10:11], s[6:7]
	s_cbranch_execz .LBB0_1262
	v_readlane_b32 s16, v253, 2
	v_readlane_b32 s18, v253, 4
	v_readlane_b32 s19, v253, 5
	s_mov_b32 s16, 0xbfb8aa3b
	v_readlane_b32 s17, v253, 3
	v_lshl_add_u64 v[0:1], s[18:19], 0, v[22:23]
	global_load_dword v2, v[0:1], off
	global_load_dword v3, v[16:17], off
	s_waitcnt vmcnt(0)
	v_add_f32_e32 v2, v2, v3
	v_mul_f32_e64 v3, |v2|, s16
	v_exp_f32_e32 v3, v3
	v_min_f32_e32 v2, 0, v2
	v_add_f32_e32 v3, 1.0, v3
	v_log_f32_e32 v3, v3
	s_nop 0
	v_fmac_f32_e32 v2, 0xbf317218, v3
	global_store_dword v[0:1], v2, off
	s_branch .LBB0_1262
